# static s_setprio 1 for waves 4-7 (younger half) around the gla_s1 and gla_s3 unit loops, reset to 0 at phase exit (doc 7.4)
# speedup vs baseline: 1.0059x; 1.0059x over previous
.LBB0_603:
	s_or_b64 exec, exec, s[0:1]
	v_readlane_b32 s62, v253, 42
	v_readlane_b32 s0, v254, 40
	v_readlane_b32 s76, v254, 51
	v_readlane_b32 s88, v253, 17
	v_readlane_b32 s86, v254, 48
	v_readlane_b32 s34, v254, 39
	v_readlane_b32 s63, v253, 43
	s_cmpk_lt_i32 s0, 0x3e6
	v_readlane_b32 s74, v254, 50
	v_readlane_b32 s77, v254, 52
	v_readlane_b32 s89, v253, 18
	v_readlane_b32 s92, v253, 21
	v_readlane_b32 s93, v253, 22
	v_readlane_b32 s94, v253, 23
	v_readlane_b32 s95, v253, 24
	s_mov_b32 s75, 0xfffe0
	v_readlane_b32 s87, v254, 49
	s_waitcnt lgkmcnt(0)
	s_barrier
	v_readlane_b32 s90, v253, 19
	v_readlane_b32 s91, v253, 20
	s_cbranch_scc0 .LBB0_621
	v_readlane_b32 s4, v253, 44
	s_mov_b64 s[0:1], s[92:93]
	s_mov_b64 s[6:7], s[94:95]
	v_mov_b32_e32 v112, v193
	v_readlane_b32 s0, v254, 35
	v_readlane_b32 s1, v254, 36
	v_readlane_b32 s90, v254, 61
	s_andn2_b64 vcc, exec, s[0:1]
	v_readfirstlane_b32 s0, v112
	v_readlane_b32 s91, v254, 62
	s_cbranch_vccnz .LBB0_622
	s_ashr_i32 s8, s0, 8
	s_lshr_b32 s0, s0, 1
	s_and_b32 s14, s0, 0x60
	v_ashrrev_i32_e32 v113, 31, v112
	s_add_u32 s4, s6, 0x28600000
	v_lshl_add_u64 v[0:1], v[112:113], 4, s[6:7]
	s_mov_b64 s[0:1], 0x27600000
	s_addc_u32 s5, s7, 0
	v_and_b32_e32 v4, 31, v112
	s_lshl_b32 s17, s8, 7
	v_and_b32_e32 v2, 63, v112
	v_bfe_u32 v3, v112, 5, 1
	v_lshl_add_u64 v[114:115], v[0:1], 0, s[0:1]
	v_lshl_add_u64 v[0:1], v[112:113], 2, s[6:7]
	s_mov_b64 s[10:11], 0x2a600000
	s_lshl_b32 s15, s8, 9
	s_lshl_b32 s16, s8, 14
	s_ashr_i32 s18, s17, 31
	v_lshlrev_b32_e32 v160, 2, v4
	s_movk_i32 s0, 0x100
	v_lshl_add_u64 v[116:117], v[0:1], 0, s[10:11]
	v_lshlrev_b32_e32 v5, 3, v2
	v_lshlrev_b32_e32 v118, 2, v3
	v_lshl_add_u64 v[0:1], s[6:7], 0, v[160:161]
	s_mov_b64 s[8:9], 0x2ac00000
	s_add_u32 s6, s6, 0x2a700000
	v_cmp_gt_i32_e64 s[0:1], s0, v112
	v_lshlrev_b32_e32 v113, 4, v3
	v_lshlrev_b32_e32 v119, 4, v2
	v_lshl_add_u64 v[120:121], v[0:1], 0, s[8:9]
	v_or_b32_e32 v122, 1, v118
	v_or_b32_e32 v124, 2, v118
	v_or_b32_e32 v126, 3, v118
	v_or_b32_e32 v128, 8, v118
	v_or_b32_e32 v130, 9, v118
	v_or_b32_e32 v132, 10, v118
	v_or_b32_e32 v134, 11, v118
	v_or_b32_e32 v136, 16, v118
	v_or_b32_e32 v138, 17, v118
	v_or_b32_e32 v140, 18, v118
	v_or_b32_e32 v142, 19, v118
	v_or_b32_e32 v144, 24, v118
	v_or_b32_e32 v146, 25, v118
	v_or_b32_e32 v148, 26, v118
	v_or_b32_e32 v150, 27, v118
	s_addc_u32 s7, s7, 0
	v_lshlrev_b32_e32 v123, 1, v5
	v_readlane_b32 s19, v253, 41
	v_readfirstlane_b32 s32, v193
	s_nop 3
	s_lshr_b32 s32, s32, 6
	s_cmp_ge_u32 s32, 4
	s_cbranch_scc0 .Lmy_prio_s1
	s_setprio 1
.Lmy_prio_s1:
	s_branch .LBB0_607
.LBB0_606:
	s_or_b64 exec, exec, s[8:9]
	s_waitcnt lgkmcnt(0)
	s_barrier
	s_add_i32 s19, s19, s96
	s_cmpk_gt_i32 s19, 0xef
	s_cbranch_scc1 .LBB0_622

.LBB0_622:
	s_setprio 0
	s_waitcnt vmcnt(0)
	v_mov_b32_e32 v0, v193
	s_waitcnt lgkmcnt(0)
	s_barrier
	s_nop 0
	v_cmp_eq_u32_e32 vcc, 0, v0
	s_and_saveexec_b64 s[0:1], vcc
	s_cbranch_execz .LBB0_674
	v_mov_b32_e32 v0, 0x23fc0
	s_waitcnt vmcnt(0) expcnt(0) lgkmcnt(0)
	ds_read_b32 v2, v0
	ds_read_b32 v0, v252
	s_waitcnt lgkmcnt(1)
	v_cmp_ne_u32_e32 vcc, 0, v2
	s_cbranch_vccnz .LBB0_638
	s_mov_b32 s10, 1
	s_branch .LBB0_626

.LBB0_731:
	s_or_b64 exec, exec, s[0:1]
	v_readlane_b32 s0, v254, 40
	s_cmpk_lt_i32 s0, 0x3e4
	s_waitcnt lgkmcnt(0)
	s_barrier
	s_cbranch_scc0 .LBB0_808
	s_mov_b64 s[4:5], s[94:95]
	v_readlane_b32 s6, v253, 44
	s_mov_b64 s[0:1], s[92:93]
	v_mov_b32_e32 v0, v193
	v_readlane_b32 s0, v254, 29
	v_readlane_b32 s1, v254, 30
	s_andn2_b64 vcc, exec, s[0:1]
	v_readfirstlane_b32 s0, v0
	s_cbranch_vccnz .LBB0_749
	s_ashr_i32 s12, s0, 6
	s_add_u32 s8, s4, 0x28600000
	v_ashrrev_i32_e32 v1, 31, v0
	s_addc_u32 s9, s5, 0
	v_lshl_add_u64 v[2:3], v[0:1], 4, s[4:5]
	s_mov_b64 s[6:7], 0x26600000
	s_ashr_i32 s14, s0, 8
	s_and_b32 s13, s12, 3
	v_lshl_add_u64 v[170:171], v[2:3], 0, s[6:7]
	s_mov_b64 s[6:7], 0x27600000
	v_and_b32_e32 v8, 31, v0
	s_lshl_b32 s19, s14, 7
	s_lshl_b32 s10, s14, 5
	s_lshl_b32 s18, s13, 5
	v_lshl_add_u64 v[172:173], v[2:3], 0, s[6:7]
	v_lshl_add_u64 v[2:3], v[0:1], 2, s[4:5]
	s_mov_b64 s[6:7], 0x2a600000
	s_ashr_i32 s20, s19, 31
	v_lshlrev_b32_e32 v160, 2, v8
	s_ashr_i32 s11, s10, 31
	v_lshl_add_u64 v[174:175], v[2:3], 0, s[6:7]
	v_lshl_add_u64 v[2:3], s[4:5], 0, v[160:161]
	s_mov_b64 s[6:7], 0x2cc00000
	s_cmp_lt_u32 s12, 4
	v_lshl_add_u64 v[178:179], v[2:3], 0, s[6:7]
	s_cselect_b64 s[6:7], -1, 0
	s_and_b32 s15, s12, 0xffffc
	s_sub_i32 s13, s13, s15
	v_and_b32_e32 v6, 63, v0
	s_lshl_b32 s13, s13, 12
	v_bfe_u32 v7, v0, 5, 1
	v_lshlrev_b32_e32 v1, 2, v6
	s_add_i32 s13, s13, 0x18000
	s_movk_i32 s0, 0x100
	v_or_b32_e32 v2, s10, v8
	v_mov_b32_e32 v3, s11
	v_lshlrev_b32_e32 v210, 4, v7
	v_mov_b32_e32 v211, v161
	v_lshlrev_b32_e32 v9, 3, v6
	v_lshlrev_b32_e32 v10, 4, v6
	v_or_b32_e32 v6, 0x18000, v1
	v_or_b32_e32 v181, s13, v1
	v_mov_b32_e32 v1, 0x20000
	v_cmp_gt_i32_e64 s[0:1], s0, v0
	v_lshlrev_b32_e32 v177, 4, v0
	v_lshl_add_u64 v[4:5], s[4:5], 0, v[210:211]
	v_lshl_add_u32 v185, v0, 2, v1
	v_lshlrev_b64 v[0:1], 7, v[2:3]
	v_lshl_add_u64 v[0:1], v[4:5], 0, v[0:1]
	s_mov_b64 s[16:17], 0x2a800000
	v_lshl_add_u64 v[212:213], v[0:1], 0, s[16:17]
	v_lshlrev_b32_e32 v0, 14, v7
	s_lshl_b64 s[10:11], s[10:11], 12
	v_lshlrev_b32_e32 v1, 1, v8
	v_lshlrev_b32_e32 v176, 2, v7
	s_lshl_b32 s12, s12, 12
	s_lshl_b32 s21, s14, 9
	v_or_b32_e32 v11, 0x10000, v10
	s_lshl_b32 s13, s14, 14
	v_or3_b32 v0, s10, v0, v1
	v_mov_b32_e32 v1, s11
	v_or_b32_e32 v180, 1, v176
	v_or_b32_e32 v182, 2, v176
	v_or_b32_e32 v184, 3, v176
	v_or_b32_e32 v186, 8, v176
	v_or_b32_e32 v188, 9, v176
	v_or_b32_e32 v190, 10, v176
	v_or_b32_e32 v192, 11, v176
	v_or_b32_e32 v194, 16, v176
	v_or_b32_e32 v196, 17, v176
	v_or_b32_e32 v198, 18, v176
	v_or_b32_e32 v200, 19, v176
	v_or_b32_e32 v202, 24, v176
	v_or_b32_e32 v204, 25, v176
	v_or_b32_e32 v206, 26, v176
	v_or_b32_e32 v208, 27, v176
	v_add_u32_e32 v183, 0x10000, v177
	s_add_i32 s21, s21, 0x20000
	v_lshl_or_b32 v187, s14, 13, v10
	v_lshl_add_u64 v[214:215], s[4:5], 0, v[0:1]
	v_lshlrev_b32_e32 v189, 1, v9
	v_add_u32_e32 v191, s12, v6
	v_add_u32_e32 v199, s13, v11
	v_readlane_b32 s22, v254, 41
	v_readlane_b32 s23, v253, 41
	v_readfirstlane_b32 s32, v193
	s_nop 3
	s_lshr_b32 s32, s32, 6
	s_cmp_ge_u32 s32, 4
	s_cbranch_scc0 .Lmy_prio_s3
	s_setprio 1
.Lmy_prio_s3:
	s_branch .LBB0_735
.LBB0_734:
	v_readlane_b32 s4, v254, 42
	s_add_i32 s23, s23, s96
	s_add_i32 s22, s22, s4
	s_cmpk_gt_i32 s23, 0xff
	s_cbranch_scc1 .LBB0_749
